# ntconv plus write-through KV / M2 outputs and non-temporal M2 scan loads
# baseline (speedup 1.0000x reference)
; __device__ __forceinline__ unsigned pk2(float lo, float hi) { return pg8::cvt_pk_bf16(lo, hi); }
; __device__ __forceinline__ float ret_lg2(int h) { return log2f(1.0f - exp2f(-5.0f - (float)h)); }
; __device__ __forceinline__ void m2_scans(const Args& a, int l, int tid, int G) {
;     ...
;     for (int r = gt; r < 8 * 8192; r += NRT) {
;         const int bh = r >> 13, ed = (r & 8191) * 2, h = bh & 3;
;         const float gC = exp2f(128.0f * ret_lg2(h));
;         const float* p = (const float*)(a.ws + WS_KV) + (size_t)bh * 64 * 16384 + ed; bf16* pb = (bf16*)(a.ws + WS_PB) + (size_t)bh * 64 * 16384 + ed;
;         float S0 = 0.f, S1 = 0.f;
;         for (int nb = 0; nb < 64; nb += 32) {
;             f32x2 v[32];
; #pragma unroll
;             for (int j = 0; j < 32; ++j) v[j] = *(const f32x2*)(p + (size_t)(nb + j) * 16384);
; #pragma unroll
;             for (int j = 0; j < 32; ++j) { *(unsigned*)(pb + (size_t)(nb + j) * 16384) = pk2(S0, S1); S0 = fmaf(gC, S0, v[j].x); S1 = fmaf(gC, S1, v[j].y); }
;         }
.LBB0_1377:
	v_cndmask_b32_e64 v8, 0, 1, s[4:5]
	s_or_b32 s74, s82, 0x4000
	v_cmp_ne_u32_e32 vcc, 1, v8
	v_lshl_add_u64 v[8:9], s[82:83], 2, v[2:3]
	s_mov_b32 s75, s83
	s_or_b32 s76, s82, 0x8000
	global_load_dwordx2 v[8:9], v[8:9], off nt
	v_lshl_add_u64 v[10:11], s[74:75], 2, v[2:3]
	s_mov_b32 s77, s83
	s_or_b32 s88, s82, 0xc000
	global_load_dwordx2 v[10:11], v[10:11], off nt
	v_lshl_add_u64 v[12:13], s[76:77], 2, v[2:3]
	s_mov_b32 s89, s83
	s_or_b32 s90, s82, 0x10000
	global_load_dwordx2 v[12:13], v[12:13], off nt
	v_lshl_add_u64 v[14:15], s[88:89], 2, v[2:3]
	s_mov_b32 s91, s83
	s_or_b32 s24, s82, 0x14000
	global_load_dwordx2 v[14:15], v[14:15], off nt
	v_lshl_add_u64 v[16:17], s[90:91], 2, v[2:3]
	s_mov_b32 s25, s83
	s_or_b32 s0, s82, 0x18000
	global_load_dwordx2 v[16:17], v[16:17], off nt
	v_lshl_add_u64 v[18:19], s[24:25], 2, v[2:3]
	s_mov_b32 s1, s83
	s_or_b32 s26, s82, 0x1c000
	global_load_dwordx2 v[18:19], v[18:19], off nt
	v_lshl_add_u64 v[20:21], s[0:1], 2, v[2:3]
	s_mov_b32 s27, s83
	s_or_b32 s78, s82, 0x20000
	global_load_dwordx2 v[20:21], v[20:21], off nt
	v_lshl_add_u64 v[22:23], s[26:27], 2, v[2:3]
	s_mov_b32 s79, s83
	s_or_b32 s80, s82, 0x24000
	s_or_b32 s52, s82, 0x2c000
	s_or_b32 s56, s82, 0x34000
	global_load_dwordx2 v[22:23], v[22:23], off nt
	v_lshl_add_u64 v[24:25], s[78:79], 2, v[2:3]
	s_mov_b32 s81, s83
	s_mov_b32 s53, s83
	s_mov_b32 s57, s83
	s_or_b32 s72, s82, 0x28000
	global_load_dwordx2 v[24:25], v[24:25], off nt
	v_lshl_add_u64 v[26:27], s[80:81], 2, v[2:3]
	s_mov_b32 s73, s83
	v_lshl_add_u64 v[30:31], s[52:53], 2, v[2:3]
	v_lshl_add_u64 v[34:35], s[56:57], 2, v[2:3]
	global_load_dwordx2 v[28:29], v[26:27], off nt
	s_or_b32 s54, s82, 0x30000
	global_load_dwordx2 v[30:31], v[30:31], off nt
	s_mov_b32 s55, s83
	global_load_dwordx2 v[34:35], v[34:35], off nt
	v_lshl_add_u64 v[26:27], s[72:73], 2, v[2:3]
	global_load_dwordx2 v[26:27], v[26:27], off nt
	v_lshl_add_u64 v[32:33], s[54:55], 2, v[2:3]
	s_or_b32 s58, s82, 0x38000
	global_load_dwordx2 v[32:33], v[32:33], off nt
	s_mov_b32 s59, s83
	s_or_b32 s60, s82, 0x3c000
	v_lshl_add_u64 v[36:37], s[58:59], 2, v[2:3]
	s_mov_b32 s61, s83
	s_or_b32 s62, s82, 0x40000
	global_load_dwordx2 v[36:37], v[36:37], off nt
	v_lshl_add_u64 v[38:39], s[60:61], 2, v[2:3]
	s_mov_b32 s63, s83
	s_or_b32 s64, s82, 0x44000
	global_load_dwordx2 v[38:39], v[38:39], off nt
	v_lshl_add_u64 v[40:41], s[62:63], 2, v[2:3]
	s_mov_b32 s65, s83
	s_or_b32 s66, s82, 0x48000
	global_load_dwordx2 v[40:41], v[40:41], off nt
	v_lshl_add_u64 v[42:43], s[64:65], 2, v[2:3]
	s_mov_b32 s67, s83
	s_or_b32 s68, s82, 0x4c000
	global_load_dwordx2 v[42:43], v[42:43], off nt
	v_lshl_add_u64 v[48:49], s[66:67], 2, v[2:3]
	s_mov_b32 s69, s83
	s_or_b32 s70, s82, 0x50000
	global_load_dwordx2 v[48:49], v[48:49], off nt
	v_lshl_add_u64 v[50:51], s[68:69], 2, v[2:3]
	s_mov_b32 s71, s83
	s_or_b32 s50, s82, 0x54000
	global_load_dwordx2 v[50:51], v[50:51], off nt
	v_lshl_add_u64 v[52:53], s[70:71], 2, v[2:3]
	s_mov_b32 s51, s83
	s_or_b32 s6, s82, 0x58000
	global_load_dwordx2 v[52:53], v[52:53], off nt
	v_lshl_add_u64 v[54:55], s[50:51], 2, v[2:3]
	s_mov_b32 s7, s83
	s_or_b32 s28, s82, 0x5c000
	global_load_dwordx2 v[54:55], v[54:55], off nt
	v_lshl_add_u64 v[56:57], s[6:7], 2, v[2:3]
	s_mov_b32 s29, s83
	s_or_b32 s30, s82, 0x60000
	global_load_dwordx2 v[56:57], v[56:57], off nt
	v_lshl_add_u64 v[58:59], s[28:29], 2, v[2:3]
	s_mov_b32 s31, s83
	s_or_b32 s34, s82, 0x64000
	global_load_dwordx2 v[58:59], v[58:59], off nt
	v_lshl_add_u64 v[60:61], s[30:31], 2, v[2:3]
	s_mov_b32 s35, s83
	s_or_b32 s40, s82, 0x68000
	global_load_dwordx2 v[60:61], v[60:61], off nt
	v_lshl_add_u64 v[62:63], s[34:35], 2, v[2:3]
	s_mov_b32 s41, s83
	s_or_b32 s42, s82, 0x6c000
	global_load_dwordx2 v[62:63], v[62:63], off nt
	v_lshl_add_u64 v[64:65], s[40:41], 2, v[2:3]
	s_mov_b32 s43, s83
	s_or_b32 s44, s82, 0x70000
	global_load_dwordx2 v[64:65], v[64:65], off nt
	v_lshl_add_u64 v[66:67], s[42:43], 2, v[2:3]
	s_mov_b32 s45, s83
	s_or_b32 s46, s82, 0x74000
	global_load_dwordx2 v[66:67], v[66:67], off nt
	v_lshl_add_u64 v[68:69], s[44:45], 2, v[2:3]
	s_mov_b32 s47, s83
	s_or_b32 s48, s82, 0x78000
	global_load_dwordx2 v[68:69], v[68:69], off nt
	v_lshl_add_u64 v[70:71], s[46:47], 2, v[2:3]
	s_mov_b32 s49, s83
	s_or_b32 s4, s82, 0x7c000
	global_load_dwordx2 v[70:71], v[70:71], off nt
	v_lshl_add_u64 v[72:73], s[48:49], 2, v[2:3]
	s_mov_b32 s5, s83
	global_load_dwordx2 v[72:73], v[72:73], off nt
	v_lshl_add_u64 v[74:75], s[4:5], 2, v[2:3]
	global_load_dwordx2 v[74:75], v[74:75], off nt
	v_cvt_pk_bf16_f32 v47, v6, v7
	v_lshl_add_u64 v[76:77], s[82:83], 1, v[4:5]
	s_waitcnt vmcnt(31)
	v_pk_fma_f32 v[6:7], v[0:1], v[6:7], v[8:9]
	global_store_dword v[76:77], v47, off sc1
	v_lshl_add_u64 v[76:77], s[74:75], 1, v[4:5]
	v_cvt_pk_bf16_f32 v8, v6, v7
	s_waitcnt vmcnt(31)
	v_pk_fma_f32 v[6:7], v[0:1], v[6:7], v[10:11]
	v_lshl_add_u64 v[78:79], s[76:77], 1, v[4:5]
	global_store_dword v[76:77], v8, off sc1
	v_cvt_pk_bf16_f32 v8, v6, v7
	s_waitcnt vmcnt(31)
	v_pk_fma_f32 v[6:7], v[0:1], v[6:7], v[12:13]
	v_lshl_add_u64 v[80:81], s[88:89], 1, v[4:5]
	global_store_dword v[78:79], v8, off sc1
	v_cvt_pk_bf16_f32 v8, v6, v7
	s_waitcnt vmcnt(31)
	v_pk_fma_f32 v[6:7], v[0:1], v[6:7], v[14:15]
	v_lshl_add_u64 v[82:83], s[90:91], 1, v[4:5]
	global_store_dword v[80:81], v8, off sc1
	v_cvt_pk_bf16_f32 v8, v6, v7
	s_waitcnt vmcnt(31)
; __device__ __forceinline__ unsigned pk2(float lo, float hi) { return pg8::cvt_pk_bf16(lo, hi); }
; __device__ __forceinline__ void m2_scans(const Args& a, int l, int tid, int G) {
;     ...
;             for (int j = 0; j < 32; ++j) v[j] = *(const f32x2*)(p + (size_t)(nb + j) * 16384);
; #pragma unroll
;             for (int j = 0; j < 32; ++j) { *(unsigned*)(pb + (size_t)(nb + j) * 16384) = pk2(S0, S1); S0 = fmaf(gC, S0, v[j].x); S1 = fmaf(gC, S1, v[j].y); }
;         }
	v_pk_fma_f32 v[6:7], v[0:1], v[6:7], v[16:17]
	v_lshl_add_u64 v[84:85], s[24:25], 1, v[4:5]
	global_store_dword v[82:83], v8, off sc1
	v_cvt_pk_bf16_f32 v8, v6, v7
	s_waitcnt vmcnt(31)
	v_pk_fma_f32 v[6:7], v[0:1], v[6:7], v[18:19]
	v_lshl_add_u64 v[86:87], s[0:1], 1, v[4:5]
	global_store_dword v[84:85], v8, off sc1
	v_cvt_pk_bf16_f32 v8, v6, v7
	s_waitcnt vmcnt(31)
	v_pk_fma_f32 v[6:7], v[0:1], v[6:7], v[20:21]
	v_lshl_add_u64 v[88:89], s[26:27], 1, v[4:5]
	global_store_dword v[86:87], v8, off sc1
	v_cvt_pk_bf16_f32 v8, v6, v7
	s_waitcnt vmcnt(31)
	v_pk_fma_f32 v[6:7], v[0:1], v[6:7], v[22:23]
	v_lshl_add_u64 v[90:91], s[78:79], 1, v[4:5]
	global_store_dword v[88:89], v8, off sc1
	v_cvt_pk_bf16_f32 v8, v6, v7
	s_waitcnt vmcnt(31)
	v_pk_fma_f32 v[6:7], v[0:1], v[6:7], v[24:25]
	v_lshl_add_u64 v[92:93], s[80:81], 1, v[4:5]
	global_store_dword v[90:91], v8, off sc1
	v_cvt_pk_bf16_f32 v8, v6, v7
	s_waitcnt vmcnt(31)
	v_pk_fma_f32 v[6:7], v[0:1], v[6:7], v[28:29]
	global_store_dword v[92:93], v8, off sc1
	v_cvt_pk_bf16_f32 v10, v6, v7
	v_lshl_add_u64 v[8:9], s[72:73], 1, v[4:5]
	s_waitcnt vmcnt(29)
	v_pk_fma_f32 v[6:7], v[0:1], v[6:7], v[26:27]
	global_store_dword v[8:9], v10, off sc1
	v_lshl_add_u64 v[8:9], s[52:53], 1, v[4:5]
	v_cvt_pk_bf16_f32 v26, v6, v7
	v_pk_fma_f32 v[6:7], v[0:1], v[6:7], v[30:31]
	v_lshl_add_u64 v[10:11], s[54:55], 1, v[4:5]
	global_store_dword v[8:9], v26, off sc1
	v_cvt_pk_bf16_f32 v8, v6, v7
	s_waitcnt vmcnt(30)
	v_pk_fma_f32 v[6:7], v[0:1], v[6:7], v[32:33]
	v_lshl_add_u64 v[12:13], s[56:57], 1, v[4:5]
	global_store_dword v[10:11], v8, off sc1
	v_cvt_pk_bf16_f32 v8, v6, v7
	v_pk_fma_f32 v[6:7], v[0:1], v[6:7], v[34:35]
	v_lshl_add_u64 v[14:15], s[58:59], 1, v[4:5]
	global_store_dword v[12:13], v8, off sc1
	v_cvt_pk_bf16_f32 v8, v6, v7
	s_waitcnt vmcnt(31)
	v_pk_fma_f32 v[6:7], v[0:1], v[6:7], v[36:37]
	v_lshl_add_u64 v[16:17], s[60:61], 1, v[4:5]
	global_store_dword v[14:15], v8, off sc1
	v_cvt_pk_bf16_f32 v8, v6, v7
	s_waitcnt vmcnt(31)
	v_pk_fma_f32 v[6:7], v[0:1], v[6:7], v[38:39]
	v_lshl_add_u64 v[18:19], s[62:63], 1, v[4:5]
	global_store_dword v[16:17], v8, off sc1
	v_cvt_pk_bf16_f32 v8, v6, v7
	s_waitcnt vmcnt(31)
	v_pk_fma_f32 v[6:7], v[0:1], v[6:7], v[40:41]
	v_lshl_add_u64 v[20:21], s[64:65], 1, v[4:5]
	global_store_dword v[18:19], v8, off sc1
	v_cvt_pk_bf16_f32 v8, v6, v7
	s_waitcnt vmcnt(31)
	v_pk_fma_f32 v[6:7], v[0:1], v[6:7], v[42:43]
	v_lshl_add_u64 v[22:23], s[66:67], 1, v[4:5]
	global_store_dword v[20:21], v8, off sc1
	v_cvt_pk_bf16_f32 v8, v6, v7
	s_waitcnt vmcnt(31)
	v_pk_fma_f32 v[6:7], v[0:1], v[6:7], v[48:49]
	v_lshl_add_u64 v[24:25], s[68:69], 1, v[4:5]
	global_store_dword v[22:23], v8, off sc1
	v_cvt_pk_bf16_f32 v8, v6, v7
	s_waitcnt vmcnt(31)
	v_pk_fma_f32 v[6:7], v[0:1], v[6:7], v[50:51]
	v_lshl_add_u64 v[28:29], s[70:71], 1, v[4:5]
	global_store_dword v[24:25], v8, off sc1
	v_cvt_pk_bf16_f32 v8, v6, v7
	s_waitcnt vmcnt(31)
	v_pk_fma_f32 v[6:7], v[0:1], v[6:7], v[52:53]
	global_store_dword v[28:29], v8, off sc1
	v_cvt_pk_bf16_f32 v10, v6, v7
	v_lshl_add_u64 v[8:9], s[50:51], 1, v[4:5]
	s_waitcnt vmcnt(31)
	v_pk_fma_f32 v[6:7], v[0:1], v[6:7], v[54:55]
	global_store_dword v[8:9], v10, off sc1
	v_lshl_add_u64 v[8:9], s[6:7], 1, v[4:5]
	v_cvt_pk_bf16_f32 v26, v6, v7
	s_waitcnt vmcnt(31)
	v_pk_fma_f32 v[6:7], v[0:1], v[6:7], v[56:57]
	v_lshl_add_u64 v[10:11], s[28:29], 1, v[4:5]
	global_store_dword v[8:9], v26, off sc1
	v_cvt_pk_bf16_f32 v8, v6, v7
	s_waitcnt vmcnt(31)
	v_pk_fma_f32 v[6:7], v[0:1], v[6:7], v[58:59]
	v_lshl_add_u64 v[12:13], s[30:31], 1, v[4:5]
	global_store_dword v[10:11], v8, off sc1
	v_cvt_pk_bf16_f32 v8, v6, v7
	s_waitcnt vmcnt(31)
	v_pk_fma_f32 v[6:7], v[0:1], v[6:7], v[60:61]
	v_lshl_add_u64 v[14:15], s[34:35], 1, v[4:5]
	global_store_dword v[12:13], v8, off sc1
	v_cvt_pk_bf16_f32 v8, v6, v7
	s_waitcnt vmcnt(31)
	v_pk_fma_f32 v[6:7], v[0:1], v[6:7], v[62:63]
	v_lshl_add_u64 v[16:17], s[40:41], 1, v[4:5]
	global_store_dword v[14:15], v8, off sc1
	v_cvt_pk_bf16_f32 v8, v6, v7
	s_waitcnt vmcnt(31)
	v_pk_fma_f32 v[6:7], v[0:1], v[6:7], v[64:65]
	v_lshl_add_u64 v[18:19], s[42:43], 1, v[4:5]
	global_store_dword v[16:17], v8, off sc1
	v_cvt_pk_bf16_f32 v8, v6, v7
	s_waitcnt vmcnt(31)
	v_pk_fma_f32 v[6:7], v[0:1], v[6:7], v[66:67]
	v_lshl_add_u64 v[20:21], s[44:45], 1, v[4:5]
	global_store_dword v[18:19], v8, off sc1
	v_cvt_pk_bf16_f32 v8, v6, v7
	s_waitcnt vmcnt(31)
	v_pk_fma_f32 v[6:7], v[0:1], v[6:7], v[68:69]
	v_lshl_add_u64 v[22:23], s[46:47], 1, v[4:5]
	global_store_dword v[20:21], v8, off sc1
	v_cvt_pk_bf16_f32 v8, v6, v7
	s_waitcnt vmcnt(31)
	v_pk_fma_f32 v[6:7], v[0:1], v[6:7], v[70:71]
	v_lshl_add_u64 v[24:25], s[48:49], 1, v[4:5]
	global_store_dword v[22:23], v8, off sc1
	v_cvt_pk_bf16_f32 v8, v6, v7
	s_waitcnt vmcnt(31)
	v_pk_fma_f32 v[6:7], v[0:1], v[6:7], v[72:73]
	global_store_dword v[24:25], v8, off sc1
	v_cvt_pk_bf16_f32 v10, v6, v7
	v_lshl_add_u64 v[8:9], s[4:5], 1, v[4:5]
	s_waitcnt vmcnt(31)
	v_pk_fma_f32 v[6:7], v[0:1], v[6:7], v[74:75]
	s_mov_b32 s82, 0x80000
	s_mov_b64 s[4:5], 0
	global_store_dword v[8:9], v10, off sc1
	s_cbranch_vccz .LBB0_1377
	v_readlane_b32 s0, v252, 58
	s_nop 1
	v_add_u32_e32 v46, s0, v46
	s_mov_b32 s0, 0xffff
	v_cmp_lt_i32_e32 vcc, s0, v46
	s_or_b64 s[38:39], vcc, s[38:39]
	s_andn2_b64 exec, exec, s[38:39]
	s_cbranch_execnz .LBB0_1376

; __device__ __forceinline__ void m2_scans(const Args& a, int l, int tid, int G) {
;     ...
;         for (int nb = 0; nb < 128; nb += 32) {
;             float av[32], hv[32];
; #pragma unroll
;             for (int j = 0; j < 32; ++j) { const size_t o = (size_t)(b * 128 + nb + j) * 256 + ch; av[j] = AE[o]; hv[j] = HE[o]; }
; #pragma unroll
;             for (int j = 0; j < 32; ++j) { const size_t o = (size_t)(b * 128 + nb + j) * 256 + ch; HE[o] = hcar; hcar = fmaf(av[j], hcar, hv[j]); }
.LBB0_1382:
	v_add_co_u32_e32 v4, vcc, 0xfffb9000, v0
	s_mov_b32 s1, 0xfffba000
	s_nop 0
	v_addc_co_u32_e32 v5, vcc, -1, v1, vcc
	global_load_dword v9, v[4:5], off offset:-3072 nt
	v_add_co_u32_e32 v2, vcc, 0xffff9000, v0
	s_add_i32 s0, s0, 32
	s_nop 0
	v_addc_co_u32_e32 v3, vcc, -1, v1, vcc
	v_add_co_u32_e32 v6, vcc, s1, v0
	global_load_dword v20, v[2:3], off offset:-3072 nt
	global_load_dword v21, v[4:5], off offset:-2048 nt
	global_load_dword v22, v[2:3], off offset:-2048 nt
	global_load_dword v23, v[4:5], off offset:-1024 nt
	global_load_dword v24, v[2:3], off offset:-1024 nt
	global_load_dword v25, v[4:5], off nt
	global_load_dword v26, v[2:3], off nt
	v_addc_co_u32_e32 v7, vcc, -1, v1, vcc
	global_load_dword v27, v[6:7], off offset:-3072 nt
	v_add_co_u32_e32 v4, vcc, 0xffffa000, v0
	s_movk_i32 s1, 0xc000
	s_nop 0
	v_addc_co_u32_e32 v5, vcc, -1, v1, vcc
	v_add_co_u32_e32 v10, vcc, 0xfffbb000, v0
	global_load_dword v28, v[4:5], off offset:-3072 nt
	global_load_dword v29, v[6:7], off offset:-2048 nt
	global_load_dword v30, v[4:5], off offset:-2048 nt
	global_load_dword v31, v[6:7], off offset:-1024 nt
	global_load_dword v32, v[4:5], off offset:-1024 nt
	global_load_dword v33, v[6:7], off nt
	global_load_dword v34, v[4:5], off nt
	v_addc_co_u32_e32 v11, vcc, -1, v1, vcc
	global_load_dword v35, v[10:11], off offset:-3072 nt
	v_add_co_u32_e32 v6, vcc, 0xffffb000, v0
	s_mov_b64 s[24:25], 0x8000
	s_nop 0
	v_addc_co_u32_e32 v7, vcc, -1, v1, vcc
	global_load_dword v36, v[6:7], off offset:-3072 nt
	global_load_dword v37, v[10:11], off offset:-2048 nt
	global_load_dword v38, v[6:7], off offset:-2048 nt
	global_load_dword v39, v[10:11], off offset:-1024 nt
	global_load_dword v40, v[6:7], off offset:-1024 nt
	global_load_dword v41, v[10:11], off nt
	global_load_dword v42, v[6:7], off nt
	v_add_co_u32_e32 v10, vcc, 0xfffbc000, v0
	s_cmpk_lt_u32 s0, 0x60
	s_nop 0
	v_addc_co_u32_e32 v11, vcc, -1, v1, vcc
	global_load_dword v43, v[10:11], off offset:-3072 nt
	v_add_co_u32_e32 v12, vcc, s1, v0
	s_movk_i32 s1, 0xe000
	s_nop 0
	v_addc_co_u32_e32 v13, vcc, -1, v1, vcc
	global_load_dword v44, v[12:13], off offset:-3072 nt
	global_load_dword v45, v[10:11], off offset:-2048 nt
	global_load_dword v46, v[12:13], off offset:-2048 nt
	global_load_dword v47, v[10:11], off offset:-1024 nt
	global_load_dword v48, v[12:13], off offset:-1024 nt
	global_load_dword v49, v[10:11], off nt
	global_load_dword v50, v[12:13], off nt
	v_add_co_u32_e32 v10, vcc, 0xfffbd000, v0
	s_waitcnt vmcnt(30)
	v_fmac_f32_e32 v20, v9, v8
	v_addc_co_u32_e32 v11, vcc, -1, v1, vcc
	global_load_dword v51, v[10:11], off offset:-3072 nt
	v_add_co_u32_e32 v14, vcc, 0xffffd000, v0
	s_waitcnt vmcnt(29)
	v_fmac_f32_e32 v22, v21, v20
	v_addc_co_u32_e32 v15, vcc, -1, v1, vcc
	global_load_dword v52, v[14:15], off offset:-3072 nt
	global_load_dword v53, v[10:11], off offset:-2048 nt
	global_load_dword v54, v[14:15], off offset:-2048 nt
	global_load_dword v55, v[10:11], off offset:-1024 nt
	global_load_dword v56, v[14:15], off offset:-1024 nt
	global_load_dword v57, v[10:11], off nt
	global_load_dword v58, v[14:15], off nt
	v_add_co_u32_e32 v10, vcc, 0xfffbe000, v0
	s_waitcnt vmcnt(34)
	v_fmac_f32_e32 v24, v23, v22
	v_addc_co_u32_e32 v11, vcc, -1, v1, vcc
	global_load_dword v59, v[10:11], off offset:-3072 nt
	v_add_co_u32_e32 v16, vcc, s1, v0
	s_waitcnt vmcnt(33)
	v_fmac_f32_e32 v26, v25, v24
	v_addc_co_u32_e32 v17, vcc, -1, v1, vcc
	global_load_dword v60, v[16:17], off offset:-3072 nt
	global_load_dword v61, v[10:11], off offset:-2048 nt
	global_load_dword v62, v[16:17], off offset:-2048 nt
	global_load_dword v63, v[10:11], off offset:-1024 nt
	global_load_dword v64, v[16:17], off offset:-1024 nt
	global_load_dword v65, v[10:11], off nt
	global_load_dword v66, v[16:17], off nt
	v_add_co_u32_e32 v10, vcc, 0xfffbf000, v0
	s_waitcnt vmcnt(38)
	v_fmac_f32_e32 v28, v27, v26
	v_addc_co_u32_e32 v11, vcc, -1, v1, vcc
	global_load_dword v67, v[10:11], off offset:-3072 nt
	v_add_co_u32_e32 v18, vcc, 0xfffff000, v0
	s_waitcnt vmcnt(37)
; __device__ __forceinline__ void m2_scans(const Args& a, int l, int tid, int G) {
;     ...
;             for (int j = 0; j < 32; ++j) { const size_t o = (size_t)(b * 128 + nb + j) * 256 + ch; av[j] = AE[o]; hv[j] = HE[o]; }
; #pragma unroll
;             for (int j = 0; j < 32; ++j) { const size_t o = (size_t)(b * 128 + nb + j) * 256 + ch; HE[o] = hcar; hcar = fmaf(av[j], hcar, hv[j]); }
;         }
	v_fmac_f32_e32 v30, v29, v28
	v_addc_co_u32_e32 v19, vcc, -1, v1, vcc
	global_load_dword v68, v[18:19], off offset:-3072 nt
	global_load_dword v69, v[10:11], off offset:-2048 nt
	global_load_dword v70, v[18:19], off offset:-2048 nt
	global_load_dword v71, v[10:11], off offset:-1024 nt
	global_load_dword v72, v[18:19], off offset:-1024 nt
	global_load_dword v73, v[10:11], off nt
	global_load_dword v74, v[0:1], off offset:-4096 nt
	v_add_co_u32_e32 v10, vcc, 0xfffc0000, v0
	s_waitcnt vmcnt(42)
	v_fmac_f32_e32 v32, v31, v30
	v_addc_co_u32_e32 v11, vcc, -1, v1, vcc
	global_load_dword v75, v[10:11], off offset:-3072 nt
	global_load_dword v76, v[0:1], off offset:-3072 nt
	global_load_dword v77, v[10:11], off offset:-2048 nt
	global_load_dword v78, v[0:1], off offset:-2048 nt
	global_load_dword v79, v[10:11], off offset:-1024 nt
	global_load_dword v80, v[0:1], off offset:-1024 nt
	s_nop 0
	global_load_dword v10, v[10:11], off nt
	s_nop 0
	global_load_dword v11, v[0:1], off nt
	s_waitcnt vmcnt(48)
	v_fmac_f32_e32 v34, v33, v32
	s_waitcnt vmcnt(46)
	v_fmac_f32_e32 v36, v35, v34
	s_waitcnt vmcnt(44)
	v_fmac_f32_e32 v38, v37, v36
	s_waitcnt vmcnt(42)
	v_fmac_f32_e32 v40, v39, v38
	s_waitcnt vmcnt(40)
	v_fmac_f32_e32 v42, v41, v40
	s_waitcnt vmcnt(38)
	v_fmac_f32_e32 v44, v43, v42
	s_waitcnt vmcnt(36)
	v_fmac_f32_e32 v46, v45, v44
	s_waitcnt vmcnt(34)
	v_fmac_f32_e32 v48, v47, v46
	s_waitcnt vmcnt(32)
	v_fmac_f32_e32 v50, v49, v48
	global_store_dword v[2:3], v8, off offset:-3072 sc1
	global_store_dword v[2:3], v20, off offset:-2048 sc1
	global_store_dword v[2:3], v22, off offset:-1024 sc1
	global_store_dword v[2:3], v24, off sc1
	global_store_dword v[4:5], v26, off offset:-3072 sc1
	global_store_dword v[4:5], v28, off offset:-2048 sc1
	global_store_dword v[4:5], v30, off offset:-1024 sc1
	global_store_dword v[4:5], v32, off sc1
	global_store_dword v[6:7], v34, off offset:-3072 sc1
	global_store_dword v[6:7], v36, off offset:-2048 sc1
	global_store_dword v[6:7], v38, off offset:-1024 sc1
	global_store_dword v[6:7], v40, off sc1
	global_store_dword v[12:13], v42, off offset:-3072 sc1
	global_store_dword v[12:13], v44, off offset:-2048 sc1
	global_store_dword v[12:13], v46, off offset:-1024 sc1
	global_store_dword v[12:13], v48, off sc1
	global_store_dword v[14:15], v50, off offset:-3072 sc1
	s_waitcnt vmcnt(47)
	v_fmac_f32_e32 v52, v51, v50
	global_store_dword v[14:15], v52, off offset:-2048 sc1
	s_waitcnt vmcnt(46)
	v_fmac_f32_e32 v54, v53, v52
	global_store_dword v[14:15], v54, off offset:-1024 sc1
	s_waitcnt vmcnt(45)
	v_fmac_f32_e32 v56, v55, v54
	global_store_dword v[14:15], v56, off sc1
	s_waitcnt vmcnt(44)
	v_fmac_f32_e32 v58, v57, v56
	global_store_dword v[16:17], v58, off offset:-3072 sc1
	s_waitcnt vmcnt(43)
	v_fmac_f32_e32 v60, v59, v58
	global_store_dword v[16:17], v60, off offset:-2048 sc1
	s_waitcnt vmcnt(42)
	v_fmac_f32_e32 v62, v61, v60
	global_store_dword v[16:17], v62, off offset:-1024 sc1
	s_waitcnt vmcnt(41)
	v_fmac_f32_e32 v64, v63, v62
	global_store_dword v[16:17], v64, off sc1
	s_waitcnt vmcnt(40)
	v_fmac_f32_e32 v66, v65, v64
	global_store_dword v[18:19], v66, off offset:-3072 sc1
	s_waitcnt vmcnt(39)
	v_fmac_f32_e32 v68, v67, v66
	global_store_dword v[18:19], v68, off offset:-2048 sc1
	s_waitcnt vmcnt(38)
	v_fmac_f32_e32 v70, v69, v68
	global_store_dword v[18:19], v70, off offset:-1024 sc1
	s_waitcnt vmcnt(37)
	v_fmac_f32_e32 v72, v71, v70
	global_store_dword v[0:1], v72, off offset:-4096 sc1
	s_waitcnt vmcnt(36)
	v_fmac_f32_e32 v74, v73, v72
	s_waitcnt vmcnt(34)
	v_fmac_f32_e32 v76, v75, v74
	s_waitcnt vmcnt(32)
	v_fmac_f32_e32 v78, v77, v76
	global_store_dword v[0:1], v74, off offset:-3072 sc1
	s_waitcnt vmcnt(31)
	v_fmac_f32_e32 v80, v79, v78
	global_store_dword v[0:1], v76, off offset:-2048 sc1
	s_waitcnt vmcnt(30)
	v_fmac_f32_e32 v11, v10, v80
	global_store_dword v[0:1], v78, off offset:-1024 sc1
	global_store_dword v[0:1], v80, off sc1
	v_lshl_add_u64 v[0:1], v[0:1], 0, s[24:25]
	v_mov_b32_e32 v8, v11
	s_cbranch_scc1 .LBB0_1382

; __device__ __forceinline__ void m2_scans(const Args& a, int l, int tid, int G) {
;     ...
;     if (rt < 2048) {
;         const int p = rt & 63, g = (rt >> 6) & 15, b = rt >> 10;
;         const float* tab = (const float*)(a.ws + WS_W + (size_t)l * WL_STRIDE + WL_S5T) + (size_t)g * 36 * 64;
;         const float cr = tab[128 + p], ci = tab[192 + p];
;         float* E = (float*)(a.ws + WS_S5E);
;         float sre = 0.f, sim = 0.f;
;         for (int nb = 0; nb < 128; nb += 32) {
;             float er[32], ei[32];
; #pragma unroll
;             for (int j = 0; j < 32; ++j) { const size_t o = ((size_t)((b * 128 + nb + j) * 16 + g) * 2) * 64 + p; er[j] = E[o]; ei[j] = E[o + 64]; }
; #pragma unroll
;             for (int j = 0; j < 32; ++j) { const size_t o = ((size_t)((b * 128 + nb + j) * 16 + g) * 2) * 64 + p; E[o] = sre; E[o + 64] = sim;
;                 const float nre = cr * sre - ci * sim + er[j], nim = cr * sim + ci * sre + ei[j]; sre = nre; sim = nim; }
.LBB0_1384:
	s_andn2_saveexec_b64 s[4:5], s[4:5]
	s_cbranch_execz .LBB0_1387
	v_bfe_u32 v4, v44, 6, 4
	v_mul_u32_u24_e32 v0, 0x900, v4
	v_readlane_b32 s0, v254, 51
	v_and_b32_e32 v2, 63, v45
	v_lshlrev_b32_e32 v144, 2, v0
	v_readlane_b32 s1, v254, 52
	v_readlane_b32 s6, v252, 50
	v_mov_b32_e32 v12, 0
	v_lshl_add_u64 v[0:1], s[0:1], 0, v[144:145]
	v_lshlrev_b32_e32 v144, 2, v2
	v_lshl_add_u64 v[2:3], v[0:1], 0, v[144:145]
	global_load_dword v0, v[2:3], off offset:512 nt
	s_nop 0
	global_load_dword v2, v[2:3], off offset:768 nt
	v_lshlrev_b32_e32 v1, 1, v44
	v_and_b32_e32 v1, 0xfffff800, v1
	s_movk_i32 s1, 0x1f0
	v_readlane_b32 s7, v252, 51
	s_movk_i32 s0, 0xffe0
	v_or3_b32 v4, v1, v4, s1
	v_lshl_add_u64 v[6:7], s[6:7], 0, v[144:145]
	v_mov_b32_e32 v13, v12
	s_waitcnt vmcnt(1)
	v_mov_b32_e32 v1, v0
	s_waitcnt vmcnt(0)
	v_mov_b32_e32 v3, v2
	v_mov_b32_e32 v8, v0
	v_mov_b32_e32 v9, v2
	v_mov_b32_e32 v10, v2
	v_mov_b32_e32 v11, v0
.LBB0_1386:
	v_add_u32_e32 v14, 0xfffffe10, v4
	v_add_u32_e32 v16, 0xfffffe20, v4
	v_add_u32_e32 v18, 0xfffffe30, v4
	v_add_u32_e32 v20, 0xfffffe40, v4
	v_add_u32_e32 v22, 0xfffffe50, v4
	v_add_u32_e32 v24, 0xfffffe60, v4
	v_add_u32_e32 v26, 0xfffffe70, v4
	v_add_u32_e32 v28, 0xfffffe80, v4
	v_add_u32_e32 v30, 0xfffffe90, v4
	v_add_u32_e32 v32, 0xfffffea0, v4
	v_add_u32_e32 v34, 0xfffffeb0, v4
	v_add_u32_e32 v36, 0xfffffec0, v4
	v_add_u32_e32 v38, 0xfffffed0, v4
	v_add_u32_e32 v40, 0xfffffee0, v4
	v_add_u32_e32 v42, 0xfffffef0, v4
	v_add_u32_e32 v44, 0xffffff00, v4
	v_add_u32_e32 v46, 0xffffff10, v4
	v_add_u32_e32 v48, 0xffffff20, v4
	v_add_u32_e32 v50, 0xffffff30, v4
	v_add_u32_e32 v52, 0xffffff40, v4
	v_add_u32_e32 v54, 0xffffff50, v4
	v_add_u32_e32 v56, 0xffffff60, v4
	v_add_u32_e32 v58, 0xffffff70, v4
	v_add_u32_e32 v60, 0xffffff80, v4
	v_add_u32_e32 v62, 0xffffff90, v4
	v_add_u32_e32 v64, 0xffffffa0, v4
	v_add_u32_e32 v66, 0xffffffb0, v4
	v_subrev_u32_e32 v68, 64, v4
	v_subrev_u32_e32 v70, 48, v4
	v_subrev_u32_e32 v72, 32, v4
	v_add_u32_e32 v74, -16, v4
	v_ashrrev_i32_e32 v15, 31, v14
	v_ashrrev_i32_e32 v5, 31, v4
	v_pk_mul_f32 v[76:77], v[2:3], v[12:13]
	v_ashrrev_i32_e32 v17, 31, v16
	v_ashrrev_i32_e32 v19, 31, v18
	v_ashrrev_i32_e32 v21, 31, v20
	v_ashrrev_i32_e32 v23, 31, v22
	v_ashrrev_i32_e32 v25, 31, v24
	v_ashrrev_i32_e32 v27, 31, v26
	v_ashrrev_i32_e32 v29, 31, v28
	v_ashrrev_i32_e32 v31, 31, v30
	v_ashrrev_i32_e32 v33, 31, v32
	v_ashrrev_i32_e32 v35, 31, v34
	v_ashrrev_i32_e32 v37, 31, v36
	v_ashrrev_i32_e32 v39, 31, v38
	v_ashrrev_i32_e32 v41, 31, v40
	v_ashrrev_i32_e32 v43, 31, v42
	v_ashrrev_i32_e32 v45, 31, v44
	v_ashrrev_i32_e32 v47, 31, v46
	v_ashrrev_i32_e32 v49, 31, v48
	v_ashrrev_i32_e32 v51, 31, v50
	v_ashrrev_i32_e32 v53, 31, v52
	v_ashrrev_i32_e32 v55, 31, v54
	v_ashrrev_i32_e32 v57, 31, v56
	v_ashrrev_i32_e32 v59, 31, v58
	v_ashrrev_i32_e32 v61, 31, v60
	v_ashrrev_i32_e32 v63, 31, v62
	v_ashrrev_i32_e32 v65, 31, v64
	v_ashrrev_i32_e32 v67, 31, v66
	v_ashrrev_i32_e32 v69, 31, v68
	v_ashrrev_i32_e32 v71, 31, v70
	v_ashrrev_i32_e32 v73, 31, v72
	v_ashrrev_i32_e32 v75, 31, v74
	v_lshlrev_b64 v[80:81], 9, v[14:15]
	v_lshlrev_b64 v[78:79], 9, v[4:5]
	v_pk_fma_f32 v[100:101], v[0:1], v[12:13], v[76:77] op_sel:[0,0,1] op_sel_hi:[1,1,0] neg_lo:[0,0,1] neg_hi:[0,0,1]
	v_pk_fma_f32 v[76:77], v[0:1], v[12:13], v[76:77] op_sel:[0,0,1] op_sel_hi:[1,1,0]
	v_lshlrev_b64 v[16:17], 9, v[16:17]
	v_lshlrev_b64 v[18:19], 9, v[18:19]
	v_lshlrev_b64 v[20:21], 9, v[20:21]
	v_lshlrev_b64 v[22:23], 9, v[22:23]
	v_lshlrev_b64 v[24:25], 9, v[24:25]
	v_lshlrev_b64 v[26:27], 9, v[26:27]
	v_lshlrev_b64 v[28:29], 9, v[28:29]
	v_lshlrev_b64 v[30:31], 9, v[30:31]
	v_lshlrev_b64 v[32:33], 9, v[32:33]
	v_lshlrev_b64 v[34:35], 9, v[34:35]
	v_lshlrev_b64 v[36:37], 9, v[36:37]
	v_lshlrev_b64 v[38:39], 9, v[38:39]
	v_lshlrev_b64 v[40:41], 9, v[40:41]
	v_lshlrev_b64 v[42:43], 9, v[42:43]
	v_lshlrev_b64 v[44:45], 9, v[44:45]
	v_lshlrev_b64 v[46:47], 9, v[46:47]
	v_lshlrev_b64 v[48:49], 9, v[48:49]
	v_lshlrev_b64 v[50:51], 9, v[50:51]
	v_lshlrev_b64 v[82:83], 9, v[52:53]
	v_lshlrev_b64 v[54:55], 9, v[54:55]
	v_lshlrev_b64 v[86:87], 9, v[56:57]
	v_lshlrev_b64 v[58:59], 9, v[58:59]
	v_lshlrev_b64 v[88:89], 9, v[60:61]
	v_lshlrev_b64 v[62:63], 9, v[62:63]
	v_lshlrev_b64 v[64:65], 9, v[64:65]
	v_lshlrev_b64 v[92:93], 9, v[66:67]
	v_lshlrev_b64 v[68:69], 9, v[68:69]
	v_lshlrev_b64 v[96:97], 9, v[70:71]
	v_lshlrev_b64 v[72:73], 9, v[72:73]
	v_lshlrev_b64 v[102:103], 9, v[74:75]
	v_lshl_add_u64 v[108:109], v[6:7], 0, v[80:81]
	v_lshl_add_u64 v[14:15], v[6:7], 0, v[78:79]
	v_mov_b32_e32 v101, v77
	v_lshl_add_u64 v[110:111], v[6:7], 0, v[16:17]
	v_lshl_add_u64 v[112:113], v[6:7], 0, v[18:19]
	v_lshl_add_u64 v[114:115], v[6:7], 0, v[20:21]
	v_lshl_add_u64 v[116:117], v[6:7], 0, v[22:23]
	v_lshl_add_u64 v[118:119], v[6:7], 0, v[24:25]
	v_lshl_add_u64 v[104:105], v[6:7], 0, v[26:27]
	v_lshl_add_u64 v[98:99], v[6:7], 0, v[28:29]
	v_lshl_add_u64 v[94:95], v[6:7], 0, v[30:31]
	v_lshl_add_u64 v[90:91], v[6:7], 0, v[32:33]
	v_lshl_add_u64 v[84:85], v[6:7], 0, v[34:35]
	v_lshl_add_u64 v[80:81], v[6:7], 0, v[36:37]
	v_lshl_add_u64 v[74:75], v[6:7], 0, v[38:39]
	v_lshl_add_u64 v[70:71], v[6:7], 0, v[40:41]
	v_lshl_add_u64 v[66:67], v[6:7], 0, v[42:43]
	v_lshl_add_u64 v[60:61], v[6:7], 0, v[44:45]
	v_lshl_add_u64 v[56:57], v[6:7], 0, v[46:47]
	v_lshl_add_u64 v[52:53], v[6:7], 0, v[48:49]
	v_lshl_add_u64 v[48:49], v[6:7], 0, v[50:51]
	v_lshl_add_u64 v[44:45], v[6:7], 0, v[82:83]
	v_lshl_add_u64 v[38:39], v[6:7], 0, v[54:55]
	v_lshl_add_u64 v[34:35], v[6:7], 0, v[86:87]
	v_lshl_add_u64 v[32:33], v[6:7], 0, v[58:59]
	v_lshl_add_u64 v[30:31], v[6:7], 0, v[88:89]
; __device__ __forceinline__ void m2_scans(const Args& a, int l, int tid, int G) {
;     ...
;         for (int nb = 0; nb < 128; nb += 32) {
;             float er[32], ei[32];
; #pragma unroll
;             for (int j = 0; j < 32; ++j) { const size_t o = ((size_t)((b * 128 + nb + j) * 16 + g) * 2) * 64 + p; er[j] = E[o]; ei[j] = E[o + 64]; }
; #pragma unroll
;             for (int j = 0; j < 32; ++j) { const size_t o = ((size_t)((b * 128 + nb + j) * 16 + g) * 2) * 64 + p; E[o] = sre; E[o + 64] = sim;
;                 const float nre = cr * sre - ci * sim + er[j], nim = cr * sim + ci * sre + ei[j]; sre = nre; sim = nim; }
	v_lshl_add_u64 v[28:29], v[6:7], 0, v[62:63]
	v_lshl_add_u64 v[26:27], v[6:7], 0, v[64:65]
	v_lshl_add_u64 v[24:25], v[6:7], 0, v[92:93]
	v_lshl_add_u64 v[22:23], v[6:7], 0, v[68:69]
	v_lshl_add_u64 v[20:21], v[6:7], 0, v[96:97]
	v_lshl_add_u64 v[18:19], v[6:7], 0, v[72:73]
	v_lshl_add_u64 v[16:17], v[6:7], 0, v[102:103]
	global_load_dword v120, v[108:109], off nt
	global_load_dword v121, v[108:109], off offset:256 nt
	global_load_dword v122, v[110:111], off nt
	global_load_dword v123, v[110:111], off offset:256 nt
	global_load_dword v124, v[112:113], off nt
	global_load_dword v125, v[112:113], off offset:256 nt
	global_load_dword v126, v[114:115], off nt
	global_load_dword v127, v[114:115], off offset:256 nt
	global_load_dword v128, v[116:117], off nt
	global_load_dword v129, v[116:117], off offset:256 nt
	global_load_dword v130, v[118:119], off nt
	global_load_dword v131, v[118:119], off offset:256 nt
	global_load_dword v132, v[104:105], off nt
	global_load_dword v133, v[104:105], off offset:256 nt
	global_load_dword v134, v[98:99], off nt
	global_load_dword v135, v[98:99], off offset:256 nt
	global_load_dword v136, v[94:95], off nt
	global_load_dword v137, v[94:95], off offset:256 nt
	global_load_dword v138, v[90:91], off nt
	global_load_dword v139, v[90:91], off offset:256 nt
	global_load_dword v141, v[84:85], off nt
	global_load_dword v140, v[84:85], off offset:256 nt
	global_load_dword v143, v[80:81], off nt
	global_load_dword v142, v[80:81], off offset:256 nt
	global_load_dword v107, v[74:75], off nt
	global_load_dword v106, v[74:75], off offset:256 nt
	global_load_dword v103, v[70:71], off nt
	global_load_dword v102, v[70:71], off offset:256 nt
	global_load_dword v97, v[66:67], off nt
	global_load_dword v96, v[66:67], off offset:256 nt
	global_load_dword v93, v[60:61], off nt
	global_load_dword v92, v[60:61], off offset:256 nt
	global_load_dword v89, v[56:57], off nt
	global_load_dword v88, v[56:57], off offset:256 nt
	global_load_dword v87, v[52:53], off nt
	global_load_dword v86, v[52:53], off offset:256 nt
	global_load_dword v83, v[48:49], off nt
	global_load_dword v82, v[48:49], off offset:256 nt
	global_load_dword v77, v[44:45], off nt
	global_load_dword v76, v[44:45], off offset:256 nt
	global_load_dword v73, v[38:39], off nt
	global_load_dword v72, v[38:39], off offset:256 nt
	global_load_dword v68, v[34:35], off nt
	global_load_dword v69, v[34:35], off offset:256 nt
	global_load_dword v64, v[32:33], off nt
	global_load_dword v65, v[32:33], off offset:256 nt
	global_load_dword v62, v[30:31], off nt
	global_load_dword v63, v[30:31], off offset:256 nt
	global_load_dword v58, v[28:29], off nt
	global_load_dword v59, v[28:29], off offset:256 nt
	global_load_dword v54, v[26:27], off nt
	global_load_dword v55, v[26:27], off offset:256 nt
	global_load_dword v50, v[24:25], off nt
	global_load_dword v51, v[24:25], off offset:256 nt
	global_load_dword v46, v[22:23], off nt
	global_load_dword v47, v[22:23], off offset:256 nt
	global_load_dword v42, v[20:21], off nt
	global_load_dword v43, v[20:21], off offset:256 nt
	global_load_dword v40, v[18:19], off nt
	global_load_dword v41, v[18:19], off offset:256 nt
	global_load_dword v36, v[16:17], off nt
	global_load_dword v37, v[16:17], off offset:256 nt
	global_load_dword v78, v[14:15], off nt
	global_load_dword v79, v[14:15], off offset:256 nt
	s_nop 0
	global_store_dword v[108:109], v12, off sc1
	global_store_dword v[108:109], v13, off offset:256 sc1
	s_add_i32 s0, s0, 32
	v_add_u32_e32 v4, 0x200, v4
	s_cmpk_gt_u32 s0, 0x5f
	s_waitcnt vmcnt(62)
	v_pk_add_f32 v[12:13], v[100:101], v[120:121]
	s_nop 0
	v_pk_mul_f32 v[100:101], v[2:3], v[12:13]
	global_store_dword v[110:111], v12, off sc1
	global_store_dword v[110:111], v13, off offset:256 sc1
	v_pk_fma_f32 v[108:109], v[0:1], v[12:13], v[100:101] op_sel:[0,0,1] op_sel_hi:[1,1,0] neg_lo:[0,0,1] neg_hi:[0,0,1]
	v_pk_fma_f32 v[12:13], v[0:1], v[12:13], v[100:101] op_sel:[0,0,1] op_sel_hi:[1,1,0]
	s_nop 0
	v_mov_b32_e32 v109, v13
	v_pk_add_f32 v[12:13], v[122:123], v[108:109]
	global_store_dword v[112:113], v12, off sc1
	global_store_dword v[112:113], v13, off offset:256 sc1
	v_pk_mul_f32 v[100:101], v[2:3], v[12:13]
	s_nop 0
	v_pk_fma_f32 v[108:109], v[0:1], v[12:13], v[100:101] op_sel:[0,0,1] op_sel_hi:[1,1,0] neg_lo:[0,0,1] neg_hi:[0,0,1]
	v_pk_fma_f32 v[12:13], v[0:1], v[12:13], v[100:101] op_sel:[0,0,1] op_sel_hi:[1,1,0]
	s_nop 0
	v_mov_b32_e32 v109, v13
	s_waitcnt vmcnt(62)
	v_pk_add_f32 v[12:13], v[124:125], v[108:109]
	global_store_dword v[114:115], v12, off sc1
	global_store_dword v[114:115], v13, off offset:256 sc1
	v_pk_mul_f32 v[100:101], v[2:3], v[12:13]
	s_nop 0
	v_pk_fma_f32 v[108:109], v[0:1], v[12:13], v[100:101] op_sel:[0,0,1] op_sel_hi:[1,1,0] neg_lo:[0,0,1] neg_hi:[0,0,1]
	v_pk_fma_f32 v[12:13], v[0:1], v[12:13], v[100:101] op_sel:[0,0,1] op_sel_hi:[1,1,0]
	s_nop 0
	v_mov_b32_e32 v109, v13
	v_pk_add_f32 v[12:13], v[126:127], v[108:109]
	global_store_dword v[116:117], v12, off sc1
	global_store_dword v[116:117], v13, off offset:256 sc1
	v_pk_mul_f32 v[100:101], v[2:3], v[12:13]
	s_nop 0
	v_pk_fma_f32 v[108:109], v[0:1], v[12:13], v[100:101] op_sel:[0,0,1] op_sel_hi:[1,1,0] neg_lo:[0,0,1] neg_hi:[0,0,1]
	v_pk_fma_f32 v[12:13], v[0:1], v[12:13], v[100:101] op_sel:[0,0,1] op_sel_hi:[1,1,0]
	s_nop 0
	v_mov_b32_e32 v109, v13
	s_waitcnt vmcnt(62)
; __device__ __forceinline__ void m2_scans(const Args& a, int l, int tid, int G) {
;     ...
;         for (int nb = 0; nb < 128; nb += 32) {
;             float er[32], ei[32];
; #pragma unroll
;             for (int j = 0; j < 32; ++j) { const size_t o = ((size_t)((b * 128 + nb + j) * 16 + g) * 2) * 64 + p; er[j] = E[o]; ei[j] = E[o + 64]; }
; #pragma unroll
;             for (int j = 0; j < 32; ++j) { const size_t o = ((size_t)((b * 128 + nb + j) * 16 + g) * 2) * 64 + p; E[o] = sre; E[o + 64] = sim;
;                 const float nre = cr * sre - ci * sim + er[j], nim = cr * sim + ci * sre + ei[j]; sre = nre; sim = nim; }
	v_pk_add_f32 v[12:13], v[128:129], v[108:109]
	global_store_dword v[118:119], v12, off sc1
	global_store_dword v[118:119], v13, off offset:256 sc1
	v_pk_mul_f32 v[100:101], v[2:3], v[12:13]
	s_nop 0
	v_pk_fma_f32 v[108:109], v[0:1], v[12:13], v[100:101] op_sel:[0,0,1] op_sel_hi:[1,1,0] neg_lo:[0,0,1] neg_hi:[0,0,1]
	v_pk_fma_f32 v[12:13], v[0:1], v[12:13], v[100:101] op_sel:[0,0,1] op_sel_hi:[1,1,0]
	s_nop 0
	v_mov_b32_e32 v109, v13
	v_pk_add_f32 v[12:13], v[130:131], v[108:109]
	global_store_dword v[104:105], v12, off sc1
	global_store_dword v[104:105], v13, off offset:256 sc1
	v_pk_mul_f32 v[100:101], v[2:3], v[12:13]
	s_nop 0
	v_pk_fma_f32 v[104:105], v[0:1], v[12:13], v[100:101] op_sel:[0,0,1] op_sel_hi:[1,1,0] neg_lo:[0,0,1] neg_hi:[0,0,1]
	v_pk_fma_f32 v[12:13], v[0:1], v[12:13], v[100:101] op_sel:[0,0,1] op_sel_hi:[1,1,0]
	s_nop 0
	v_mov_b32_e32 v105, v13
	s_waitcnt vmcnt(62)
	v_pk_add_f32 v[12:13], v[132:133], v[104:105]
	global_store_dword v[98:99], v12, off sc1
	global_store_dword v[98:99], v13, off offset:256 sc1
	v_pk_mul_f32 v[98:99], v[2:3], v[12:13]
	s_nop 0
	v_pk_fma_f32 v[100:101], v[0:1], v[12:13], v[98:99] op_sel:[0,0,1] op_sel_hi:[1,1,0] neg_lo:[0,0,1] neg_hi:[0,0,1]
	v_pk_fma_f32 v[12:13], v[0:1], v[12:13], v[98:99] op_sel:[0,0,1] op_sel_hi:[1,1,0]
	s_nop 0
	v_mov_b32_e32 v101, v13
	v_pk_add_f32 v[12:13], v[134:135], v[100:101]
	global_store_dword v[94:95], v12, off sc1
	global_store_dword v[94:95], v13, off offset:256 sc1
	v_pk_mul_f32 v[94:95], v[2:3], v[12:13]
	s_nop 0
	v_pk_fma_f32 v[98:99], v[0:1], v[12:13], v[94:95] op_sel:[0,0,1] op_sel_hi:[1,1,0] neg_lo:[0,0,1] neg_hi:[0,0,1]
	v_pk_fma_f32 v[12:13], v[0:1], v[12:13], v[94:95] op_sel:[0,0,1] op_sel_hi:[1,1,0]
	s_nop 0
	v_mov_b32_e32 v99, v13
	s_waitcnt vmcnt(62)
	v_pk_add_f32 v[12:13], v[136:137], v[98:99]
	global_store_dword v[90:91], v12, off sc1
	global_store_dword v[90:91], v13, off offset:256 sc1
	v_pk_mul_f32 v[90:91], v[2:3], v[12:13]
	s_nop 0
	v_pk_fma_f32 v[94:95], v[0:1], v[12:13], v[90:91] op_sel:[0,0,1] op_sel_hi:[1,1,0] neg_lo:[0,0,1] neg_hi:[0,0,1]
	v_pk_fma_f32 v[12:13], v[0:1], v[12:13], v[90:91] op_sel:[0,0,1] op_sel_hi:[1,1,0]
	s_nop 0
	v_mov_b32_e32 v95, v13
	v_pk_add_f32 v[12:13], v[138:139], v[94:95]
	global_store_dword v[84:85], v12, off sc1
	global_store_dword v[84:85], v13, off offset:256 sc1
	v_mul_f32_e32 v84, v8, v12
	v_mul_f32_e32 v90, v11, v13
	v_pk_fma_f32 v[84:85], v[8:9], v[12:13], v[84:85] op_sel_hi:[1,1,0] neg_lo:[1,0,0] neg_hi:[1,0,0]
	v_pk_fma_f32 v[12:13], v[10:11], v[12:13], v[90:91] op_sel_hi:[1,1,0]
	s_nop 0
	v_mov_b32_e32 v13, v85
	s_waitcnt vmcnt(62)
	v_pk_add_f32 v[12:13], v[140:141], v[12:13]
	global_store_dword v[80:81], v13, off sc1
	global_store_dword v[80:81], v12, off offset:256 sc1
	v_pk_mul_f32 v[80:81], v[2:3], v[12:13]
	s_nop 0
	v_pk_fma_f32 v[84:85], v[0:1], v[12:13], v[80:81] op_sel:[0,0,1] op_sel_hi:[1,1,0]
	v_pk_fma_f32 v[12:13], v[0:1], v[12:13], v[80:81] op_sel:[0,0,1] op_sel_hi:[1,1,0] neg_lo:[0,0,1] neg_hi:[0,0,1]
	s_nop 0
	v_mov_b32_e32 v85, v13
	v_pk_add_f32 v[12:13], v[142:143], v[84:85]
	global_store_dword v[74:75], v13, off sc1
	global_store_dword v[74:75], v12, off offset:256 sc1
	v_pk_mul_f32 v[74:75], v[2:3], v[12:13]
	s_nop 0
	v_pk_fma_f32 v[80:81], v[0:1], v[12:13], v[74:75] op_sel:[0,0,1] op_sel_hi:[1,1,0]
	v_pk_fma_f32 v[12:13], v[0:1], v[12:13], v[74:75] op_sel:[0,0,1] op_sel_hi:[1,1,0] neg_lo:[0,0,1] neg_hi:[0,0,1]
	s_nop 0
	v_mov_b32_e32 v81, v13
	s_waitcnt vmcnt(62)
	v_pk_add_f32 v[12:13], v[106:107], v[80:81]
	global_store_dword v[70:71], v13, off sc1
	global_store_dword v[70:71], v12, off offset:256 sc1
	v_pk_mul_f32 v[70:71], v[2:3], v[12:13]
	s_nop 0
	v_pk_fma_f32 v[74:75], v[0:1], v[12:13], v[70:71] op_sel:[0,0,1] op_sel_hi:[1,1,0]
	v_pk_fma_f32 v[12:13], v[0:1], v[12:13], v[70:71] op_sel:[0,0,1] op_sel_hi:[1,1,0] neg_lo:[0,0,1] neg_hi:[0,0,1]
	s_nop 0
	v_mov_b32_e32 v75, v13
	v_pk_add_f32 v[12:13], v[102:103], v[74:75]
	global_store_dword v[66:67], v13, off sc1
	global_store_dword v[66:67], v12, off offset:256 sc1
	v_pk_mul_f32 v[66:67], v[2:3], v[12:13]
	s_nop 0
	v_pk_fma_f32 v[70:71], v[0:1], v[12:13], v[66:67] op_sel:[0,0,1] op_sel_hi:[1,1,0]
	v_pk_fma_f32 v[12:13], v[0:1], v[12:13], v[66:67] op_sel:[0,0,1] op_sel_hi:[1,1,0] neg_lo:[0,0,1] neg_hi:[0,0,1]
	s_nop 0
	v_mov_b32_e32 v71, v13
	s_waitcnt vmcnt(62)
	v_pk_add_f32 v[12:13], v[96:97], v[70:71]
	global_store_dword v[60:61], v13, off sc1
	global_store_dword v[60:61], v12, off offset:256 sc1
	v_pk_mul_f32 v[60:61], v[2:3], v[12:13]
	s_nop 0
	v_pk_fma_f32 v[66:67], v[0:1], v[12:13], v[60:61] op_sel:[0,0,1] op_sel_hi:[1,1,0]
	v_pk_fma_f32 v[12:13], v[0:1], v[12:13], v[60:61] op_sel:[0,0,1] op_sel_hi:[1,1,0] neg_lo:[0,0,1] neg_hi:[0,0,1]
	s_nop 0
	v_mov_b32_e32 v67, v13
	v_pk_add_f32 v[12:13], v[92:93], v[66:67]
	global_store_dword v[56:57], v13, off sc1
	global_store_dword v[56:57], v12, off offset:256 sc1
	v_pk_mul_f32 v[56:57], v[2:3], v[12:13]
	s_nop 0
	v_pk_fma_f32 v[60:61], v[0:1], v[12:13], v[56:57] op_sel:[0,0,1] op_sel_hi:[1,1,0]
	v_pk_fma_f32 v[12:13], v[0:1], v[12:13], v[56:57] op_sel:[0,0,1] op_sel_hi:[1,1,0] neg_lo:[0,0,1] neg_hi:[0,0,1]
	s_nop 0
	v_mov_b32_e32 v61, v13
	s_waitcnt vmcnt(62)
; __device__ __forceinline__ void m2_scans(const Args& a, int l, int tid, int G) {
;     ...
;         for (int nb = 0; nb < 128; nb += 32) {
;             float er[32], ei[32];
; #pragma unroll
;             for (int j = 0; j < 32; ++j) { const size_t o = ((size_t)((b * 128 + nb + j) * 16 + g) * 2) * 64 + p; er[j] = E[o]; ei[j] = E[o + 64]; }
; #pragma unroll
;             for (int j = 0; j < 32; ++j) { const size_t o = ((size_t)((b * 128 + nb + j) * 16 + g) * 2) * 64 + p; E[o] = sre; E[o + 64] = sim;
;                 const float nre = cr * sre - ci * sim + er[j], nim = cr * sim + ci * sre + ei[j]; sre = nre; sim = nim; }
	v_pk_add_f32 v[12:13], v[88:89], v[60:61]
	global_store_dword v[52:53], v13, off sc1
	global_store_dword v[52:53], v12, off offset:256 sc1
	v_pk_mul_f32 v[52:53], v[2:3], v[12:13]
	s_nop 0
	v_pk_fma_f32 v[56:57], v[0:1], v[12:13], v[52:53] op_sel:[0,0,1] op_sel_hi:[1,1,0]
	v_pk_fma_f32 v[12:13], v[0:1], v[12:13], v[52:53] op_sel:[0,0,1] op_sel_hi:[1,1,0] neg_lo:[0,0,1] neg_hi:[0,0,1]
	s_nop 0
	v_mov_b32_e32 v57, v13
	v_pk_add_f32 v[12:13], v[86:87], v[56:57]
	global_store_dword v[48:49], v13, off sc1
	global_store_dword v[48:49], v12, off offset:256 sc1
	v_pk_mul_f32 v[48:49], v[2:3], v[12:13]
	s_nop 0
	v_pk_fma_f32 v[52:53], v[0:1], v[12:13], v[48:49] op_sel:[0,0,1] op_sel_hi:[1,1,0]
	v_pk_fma_f32 v[12:13], v[0:1], v[12:13], v[48:49] op_sel:[0,0,1] op_sel_hi:[1,1,0] neg_lo:[0,0,1] neg_hi:[0,0,1]
	s_nop 0
	v_mov_b32_e32 v53, v13
	s_waitcnt vmcnt(62)
	v_pk_add_f32 v[12:13], v[82:83], v[52:53]
	global_store_dword v[44:45], v13, off sc1
	global_store_dword v[44:45], v12, off offset:256 sc1
	v_pk_mul_f32 v[44:45], v[2:3], v[12:13]
	s_nop 0
	v_pk_fma_f32 v[48:49], v[0:1], v[12:13], v[44:45] op_sel:[0,0,1] op_sel_hi:[1,1,0]
	v_pk_fma_f32 v[12:13], v[0:1], v[12:13], v[44:45] op_sel:[0,0,1] op_sel_hi:[1,1,0] neg_lo:[0,0,1] neg_hi:[0,0,1]
	s_nop 0
	v_mov_b32_e32 v49, v13
	v_pk_add_f32 v[12:13], v[76:77], v[48:49]
	global_store_dword v[38:39], v13, off sc1
	global_store_dword v[38:39], v12, off offset:256 sc1
	v_pk_mul_f32 v[38:39], v[2:3], v[12:13]
	s_nop 0
	v_pk_fma_f32 v[44:45], v[0:1], v[12:13], v[38:39] op_sel:[0,0,1] op_sel_hi:[1,1,0]
	v_pk_fma_f32 v[12:13], v[0:1], v[12:13], v[38:39] op_sel:[0,0,1] op_sel_hi:[1,1,0] neg_lo:[0,0,1] neg_hi:[0,0,1]
	s_nop 0
	v_mov_b32_e32 v45, v13
	s_waitcnt vmcnt(62)
	v_pk_add_f32 v[12:13], v[72:73], v[44:45]
	global_store_dword v[34:35], v13, off sc1
	global_store_dword v[34:35], v12, off offset:256 sc1
	v_mul_f32_e32 v34, v11, v13
	v_mul_f32_e32 v38, v8, v12
	v_pk_fma_f32 v[34:35], v[10:11], v[12:13], v[34:35] op_sel_hi:[1,1,0] neg_lo:[1,0,0] neg_hi:[1,0,0]
	v_pk_fma_f32 v[12:13], v[8:9], v[12:13], v[38:39] op_sel_hi:[1,1,0]
	s_nop 0
	v_mov_b32_e32 v35, v13
	v_pk_add_f32 v[12:13], v[68:69], v[34:35]
	global_store_dword v[32:33], v12, off sc1
	global_store_dword v[32:33], v13, off offset:256 sc1
	v_pk_mul_f32 v[32:33], v[2:3], v[12:13]
	s_nop 0
	v_pk_fma_f32 v[34:35], v[0:1], v[12:13], v[32:33] op_sel:[0,0,1] op_sel_hi:[1,1,0] neg_lo:[0,0,1] neg_hi:[0,0,1]
	v_pk_fma_f32 v[12:13], v[0:1], v[12:13], v[32:33] op_sel:[0,0,1] op_sel_hi:[1,1,0]
	s_nop 0
	v_mov_b32_e32 v35, v13
	s_waitcnt vmcnt(62)
	v_pk_add_f32 v[12:13], v[64:65], v[34:35]
	global_store_dword v[30:31], v12, off sc1
	global_store_dword v[30:31], v13, off offset:256 sc1
	v_pk_mul_f32 v[30:31], v[2:3], v[12:13]
	s_nop 0
	v_pk_fma_f32 v[32:33], v[0:1], v[12:13], v[30:31] op_sel:[0,0,1] op_sel_hi:[1,1,0] neg_lo:[0,0,1] neg_hi:[0,0,1]
	v_pk_fma_f32 v[12:13], v[0:1], v[12:13], v[30:31] op_sel:[0,0,1] op_sel_hi:[1,1,0]
	s_nop 0
	v_mov_b32_e32 v33, v13
	v_pk_add_f32 v[12:13], v[62:63], v[32:33]
	global_store_dword v[28:29], v12, off sc1
	global_store_dword v[28:29], v13, off offset:256 sc1
	v_pk_mul_f32 v[28:29], v[2:3], v[12:13]
	s_nop 0
	v_pk_fma_f32 v[30:31], v[0:1], v[12:13], v[28:29] op_sel:[0,0,1] op_sel_hi:[1,1,0] neg_lo:[0,0,1] neg_hi:[0,0,1]
	v_pk_fma_f32 v[12:13], v[0:1], v[12:13], v[28:29] op_sel:[0,0,1] op_sel_hi:[1,1,0]
	s_nop 0
	v_mov_b32_e32 v31, v13
	s_waitcnt vmcnt(62)
	v_pk_add_f32 v[12:13], v[58:59], v[30:31]
	global_store_dword v[26:27], v12, off sc1
	global_store_dword v[26:27], v13, off offset:256 sc1
	v_pk_mul_f32 v[26:27], v[2:3], v[12:13]
	s_nop 0
	v_pk_fma_f32 v[28:29], v[0:1], v[12:13], v[26:27] op_sel:[0,0,1] op_sel_hi:[1,1,0] neg_lo:[0,0,1] neg_hi:[0,0,1]
	v_pk_fma_f32 v[12:13], v[0:1], v[12:13], v[26:27] op_sel:[0,0,1] op_sel_hi:[1,1,0]
	s_nop 0
	v_mov_b32_e32 v29, v13
	v_pk_add_f32 v[12:13], v[54:55], v[28:29]
	global_store_dword v[24:25], v12, off sc1
	global_store_dword v[24:25], v13, off offset:256 sc1
	v_pk_mul_f32 v[24:25], v[2:3], v[12:13]
	s_nop 0
	v_pk_fma_f32 v[26:27], v[0:1], v[12:13], v[24:25] op_sel:[0,0,1] op_sel_hi:[1,1,0] neg_lo:[0,0,1] neg_hi:[0,0,1]
	v_pk_fma_f32 v[12:13], v[0:1], v[12:13], v[24:25] op_sel:[0,0,1] op_sel_hi:[1,1,0]
	s_nop 0
	v_mov_b32_e32 v27, v13
	s_waitcnt vmcnt(62)
	v_pk_add_f32 v[12:13], v[50:51], v[26:27]
	global_store_dword v[22:23], v12, off sc1
	global_store_dword v[22:23], v13, off offset:256 sc1
	v_pk_mul_f32 v[22:23], v[2:3], v[12:13]
	s_nop 0
	v_pk_fma_f32 v[24:25], v[0:1], v[12:13], v[22:23] op_sel:[0,0,1] op_sel_hi:[1,1,0] neg_lo:[0,0,1] neg_hi:[0,0,1]
	v_pk_fma_f32 v[12:13], v[0:1], v[12:13], v[22:23] op_sel:[0,0,1] op_sel_hi:[1,1,0]
	s_nop 0
	v_mov_b32_e32 v25, v13
	v_pk_add_f32 v[12:13], v[46:47], v[24:25]
	global_store_dword v[20:21], v12, off sc1
	global_store_dword v[20:21], v13, off offset:256 sc1
	v_pk_mul_f32 v[20:21], v[2:3], v[12:13]
	s_nop 0
	v_pk_fma_f32 v[22:23], v[0:1], v[12:13], v[20:21] op_sel:[0,0,1] op_sel_hi:[1,1,0] neg_lo:[0,0,1] neg_hi:[0,0,1]
	v_pk_fma_f32 v[12:13], v[0:1], v[12:13], v[20:21] op_sel:[0,0,1] op_sel_hi:[1,1,0]
	s_nop 0
	v_mov_b32_e32 v23, v13
	s_waitcnt vmcnt(62)
	v_pk_add_f32 v[12:13], v[42:43], v[22:23]
	global_store_dword v[18:19], v12, off sc1
	global_store_dword v[18:19], v13, off offset:256 sc1
	v_pk_mul_f32 v[18:19], v[2:3], v[12:13]
	s_nop 0
	v_pk_fma_f32 v[20:21], v[0:1], v[12:13], v[18:19] op_sel:[0,0,1] op_sel_hi:[1,1,0] neg_lo:[0,0,1] neg_hi:[0,0,1]
	v_pk_fma_f32 v[12:13], v[0:1], v[12:13], v[18:19] op_sel:[0,0,1] op_sel_hi:[1,1,0]
	s_nop 0
	v_mov_b32_e32 v21, v13
	v_pk_add_f32 v[12:13], v[40:41], v[20:21]
	global_store_dword v[16:17], v12, off sc1
	global_store_dword v[16:17], v13, off offset:256 sc1
	v_pk_mul_f32 v[16:17], v[2:3], v[12:13]
	s_nop 0
	v_pk_fma_f32 v[18:19], v[0:1], v[12:13], v[16:17] op_sel:[0,0,1] op_sel_hi:[1,1,0] neg_lo:[0,0,1] neg_hi:[0,0,1]
	v_pk_fma_f32 v[12:13], v[0:1], v[12:13], v[16:17] op_sel:[0,0,1] op_sel_hi:[1,1,0]
	s_nop 0
	v_mov_b32_e32 v19, v13
	s_waitcnt vmcnt(62)
	v_pk_add_f32 v[12:13], v[36:37], v[18:19]
	global_store_dword v[14:15], v12, off sc1
	global_store_dword v[14:15], v13, off offset:256 sc1
	v_pk_mul_f32 v[14:15], v[2:3], v[12:13]
	s_nop 0
	v_pk_fma_f32 v[16:17], v[0:1], v[12:13], v[14:15] op_sel:[0,0,1] op_sel_hi:[1,1,0] neg_lo:[0,0,1] neg_hi:[0,0,1]
	v_pk_fma_f32 v[12:13], v[0:1], v[12:13], v[14:15] op_sel:[0,0,1] op_sel_hi:[1,1,0]
	s_nop 0
	v_mov_b32_e32 v17, v13
	v_pk_add_f32 v[12:13], v[78:79], v[16:17]
	s_cbranch_scc0 .LBB0_1386
